# P1 MFMA issue order: snake within each group of 8 so that every consecutive MFMA pair shares one source operand (operand reuse)
# speedup vs baseline: 1.0067x; 1.0067x over previous
; #define PG8_LAS __attribute__((address_space(3)))
; #define PG8_STAGE(bufoff, gbase, voff) do { _Pragma("unroll") for (int _i = 0; _i < 2; ++_i) \
;         __builtin_amdgcn_global_load_lds((const unsigned*)((const char*)(gbase) + (voff)[_i]), (PG8_LAS unsigned*)(lds + (bufoff) + ldsw + _i * 8192), 16, 0, 0); } while (0)
; #define PG8_LDA(dst, b, h) do { _Pragma("unroll") for (int m = 0; m < 4; ++m) _Pragma("unroll") for (int k = 0; k < 2; ++k) dst[m][k] = *(const PG8_LAS bf16x8*)(lds + PG8_SA(b, h) + aoff + m * 2048 + k * 1024); } while (0)
; template <class Epi, class Sched, bool ALIGN_EPI = false, bool SP2 = false, bool RS = false, bool BPRE = false>
; __device__ __forceinline__ void gemm_phase(PG8_LAS unsigned char* lds, const Gemm g, const Sched& S, const Epi& E, const float* rs_ss = nullptr, PG8_LAS float* rs_tab = nullptr) {
;     ...
;         const bool has_next = S.next(ui + 1, nxt);
;         const char* nA = has_next ? (const char*)g.A + (size_t)nxt.pm * tstep : cA; const char* nB = has_next ? (const char*)g.Bt + (size_t)nxt.pn * tstep : cB;
;         for (int t = 0; t < nt; t += 2) {
;             const bool last = (t == nt - 2);
;             if constexpr (RS) { if (t == 16 || t == 32) { const PG8_LAS float* tp = rs_tab + (ui & 1) * 768 + (t == 32 ? 256 : 0);
;                 _Pragma("unroll") for (int a = 0; a < 2; ++a) _Pragma("unroll") for (int m = 0; m < 4; ++m) { const float f = tp[a * HALF + wr * 64 + m * 16 + fr];
;                     _Pragma("unroll") for (int b = 0; b < 2; ++b) _Pragma("unroll") for (int n = 0; n < 2; ++n) acc[a][b][m][n] = acc[a][b][m][n] * f; } } }
;             const char* a1 = cA + (size_t)(t + 1) * kstep;
;             const char* a2 = last ? nA : cA + (size_t)(t + 2) * kstep; const char* b2 = last ? nB : cB + (size_t)(t + 2) * kstep;
;             const char* a3 = a2 + kstep; const char* b3 = b2 + kstep;
;             if (last && has_next) S.a_ready(nxt);
;             if constexpr (SP2) {
;             PG8_LDB(B0, 0, 0); PG8_LDB(B1, 0, 1); PG8_SCHED; PG8_LDA(At, 0, 0); PG8_STAGE(PG8_SA(1, 1), a1 + hstep, voffA);
;             PG8_WAIT_V(8); PG8_WAIT_L(0); PG8_BAR; PG8_MMA(0, 0, At, B0); PG8_MMA(0, 1, At, B1); PG8_BAR; PG8_SCHED;
;             PG8_LDA(At, 0, 1); PG8_STAGE(PG8_SB(0, 0), b2, voffB); PG8_STAGE(PG8_SB(0, 1), b2 + hstep, voffB); PG8_STAGE(PG8_SA(0, 0), a2, voffA);
.LBB0_195:
	s_ashr_i32 s19, s18, 31
	s_lshl_b64 s[20:21], s[18:19], 20
	s_add_u32 s20, s30, s20
	s_addc_u32 s21, s31, s21
	s_and_b64 s[44:45], s[6:7], exec
	s_cselect_b32 s5, s21, s57
	s_cselect_b32 s19, s20, s56
	s_ashr_i32 s17, s16, 31
	s_lshl_b64 s[44:45], s[16:17], 20
	s_add_u32 s44, s24, s44
	s_addc_u32 s45, s25, s45
	s_and_b64 s[60:61], s[6:7], exec
	s_cselect_b32 s17, s45, s59
	s_cselect_b32 s47, s44, s58
	s_add_u32 s56, s56, 0x84000
	s_addc_u32 s57, s57, 0
	s_add_u32 s87, s58, 0x8000
	s_addc_u32 s88, s59, 0
	s_mov_b32 s89, -2
	s_waitcnt lgkmcnt(0)
	ds_read_b128 v[130:133], v161
	ds_read_b128 v[134:137], v161 offset:1024
	ds_read_b128 v[152:155], v161 offset:2048
	ds_read_b128 v[156:159], v161 offset:3072
	ds_read_b128 v[166:169], v162
	ds_read_b128 v[170:173], v162 offset:1024
	ds_read_b128 v[174:177], v162 offset:2048
	ds_read_b128 v[182:185], v162 offset:3072
	s_add_u32 s58, s56, 0xfff84000
	s_addc_u32 s59, s57, -1
	s_cmp_eq_u32 s89, 28
	s_cselect_b32 s70, s19, s58
	s_cselect_b32 s71, s5, s59
	s_cselect_b32 s60, s47, s87
	s_cselect_b32 s61, s17, s88
	s_add_u32 s58, s70, 0x4000
	s_addc_u32 s59, s71, 0
	v_lshl_add_u64 v[178:179], s[56:57], 0, v[138:139]
	s_add_i32 m0, s72, 0xc000
	ds_read_b128 v[186:189], v163
	ds_read_b128 v[190:193], v163 offset:1024
	ds_read_b128 v[194:197], v163 offset:2048
	ds_read_b128 v[198:201], v163 offset:3072
	ds_read_b128 v[202:205], v163 offset:4096
	ds_read_b128 v[206:209], v163 offset:5120
	ds_read_b128 v[210:213], v163 offset:6144
	ds_read_b128 v[214:217], v163 offset:7168
	global_load_lds_dwordx4 v[178:179], off
	v_lshl_add_u64 v[178:179], s[56:57], 0, v[146:147]
	s_add_i32 m0, s72, 0xe000
	s_nop 0
	global_load_lds_dwordx4 v[178:179], off
	s_waitcnt vmcnt(8)
	s_waitcnt lgkmcnt(0)
	s_barrier
	s_setprio 1
	s_waitcnt lgkmcnt(0)
	v_mfma_f32_16x16x32_bf16 v[126:129], v[130:133], v[186:189], 0
	v_mfma_f32_16x16x32_bf16 v[122:125], v[152:155], v[186:189], 0
	v_mfma_f32_16x16x32_bf16 v[106:109], v[152:155], v[194:197], 0
	v_mfma_f32_16x16x32_bf16 v[110:113], v[130:133], v[194:197], 0
	v_mfma_f32_16x16x32_bf16 v[94:97], v[130:133], v[202:205], 0
	v_mfma_f32_16x16x32_bf16 v[90:93], v[152:155], v[202:205], 0
	v_mfma_f32_16x16x32_bf16 v[74:77], v[152:155], v[210:213], 0
	v_mfma_f32_16x16x32_bf16 v[78:81], v[130:133], v[210:213], 0
	v_mfma_f32_16x16x32_bf16 v[126:129], v[134:137], v[190:193], v[126:129]
	v_mfma_f32_16x16x32_bf16 v[122:125], v[156:159], v[190:193], v[122:125]
	v_mfma_f32_16x16x32_bf16 v[106:109], v[156:159], v[198:201], v[106:109]
	v_mfma_f32_16x16x32_bf16 v[110:113], v[134:137], v[198:201], v[110:113]
	v_mfma_f32_16x16x32_bf16 v[94:97], v[134:137], v[206:209], v[94:97]
	v_mfma_f32_16x16x32_bf16 v[90:93], v[156:159], v[206:209], v[90:93]
	v_mfma_f32_16x16x32_bf16 v[74:77], v[156:159], v[214:217], v[74:77]
	v_mfma_f32_16x16x32_bf16 v[78:81], v[134:137], v[214:217], v[78:81]
	s_setprio 0
	s_setprio 1
	v_mfma_f32_16x16x32_bf16 v[118:121], v[166:169], v[186:189], 0
	v_mfma_f32_16x16x32_bf16 v[114:117], v[174:177], v[186:189], 0
	v_mfma_f32_16x16x32_bf16 v[98:101], v[174:177], v[194:197], 0
	v_mfma_f32_16x16x32_bf16 v[102:105], v[166:169], v[194:197], 0
	v_mfma_f32_16x16x32_bf16 v[86:89], v[166:169], v[202:205], 0
	v_mfma_f32_16x16x32_bf16 v[82:85], v[174:177], v[202:205], 0
	v_mfma_f32_16x16x32_bf16 v[66:69], v[174:177], v[210:213], 0
	v_mfma_f32_16x16x32_bf16 v[70:73], v[166:169], v[210:213], 0
	v_mfma_f32_16x16x32_bf16 v[118:121], v[170:173], v[190:193], v[118:121]
	v_mfma_f32_16x16x32_bf16 v[114:117], v[182:185], v[190:193], v[114:117]
	v_mfma_f32_16x16x32_bf16 v[98:101], v[182:185], v[198:201], v[98:101]
	v_mfma_f32_16x16x32_bf16 v[102:105], v[170:173], v[198:201], v[102:105]
	v_mfma_f32_16x16x32_bf16 v[86:89], v[170:173], v[206:209], v[86:89]
	v_mfma_f32_16x16x32_bf16 v[82:85], v[182:185], v[206:209], v[82:85]
	v_mfma_f32_16x16x32_bf16 v[66:69], v[182:185], v[214:217], v[66:69]
	v_mfma_f32_16x16x32_bf16 v[70:73], v[170:173], v[214:217], v[70:73]
	s_setprio 0
	s_barrier
	s_add_i32 s90, s83, s15
	v_lshl_add_u64 v[178:179], s[60:61], 0, v[138:139]
	s_mov_b32 m0, s90
	ds_read_b128 v[186:189], v163 offset:16384
	ds_read_b128 v[190:193], v163 offset:17408
	ds_read_b128 v[194:197], v163 offset:18432
	ds_read_b128 v[198:201], v163 offset:19456
	ds_read_b128 v[202:205], v163 offset:20480
	ds_read_b128 v[206:209], v163 offset:21504
	ds_read_b128 v[210:213], v163 offset:22528
	ds_read_b128 v[214:217], v163 offset:23552
	global_load_lds_dwordx4 v[178:179], off
	s_add_i32 m0, s90, 0x2000
	s_add_u32 s90, s60, 0x80000
	v_lshl_add_u64 v[178:179], s[60:61], 0, v[140:141]
	s_addc_u32 s91, s61, 0
	s_add_i32 s92, s86, s15
	global_load_lds_dwordx4 v[178:179], off
	v_lshl_add_u64 v[178:179], s[90:91], 0, v[138:139]
	s_mov_b32 m0, s92
	s_nop 0
	global_load_lds_dwordx4 v[178:179], off
	v_lshl_add_u64 v[178:179], s[90:91], 0, v[140:141]
	s_add_i32 m0, s92, 0x2000
	s_nop 0
	global_load_lds_dwordx4 v[178:179], off
	v_lshl_add_u64 v[178:179], s[70:71], 0, v[138:139]
	s_mov_b32 m0, s72
	s_nop 0
	global_load_lds_dwordx4 v[178:179], off
	v_lshl_add_u64 v[178:179], s[70:71], 0, v[140:141]
	s_mov_b32 m0, s73
	s_nop 0
	global_load_lds_dwordx4 v[178:179], off
	s_waitcnt vmcnt(8)
	s_waitcnt lgkmcnt(0)
	s_barrier
; #define PG8_STAGE(bufoff, gbase, voff) do { _Pragma("unroll") for (int _i = 0; _i < 2; ++_i) \
;         __builtin_amdgcn_global_load_lds((const unsigned*)((const char*)(gbase) + (voff)[_i]), (PG8_LAS unsigned*)(lds + (bufoff) + ldsw + _i * 8192), 16, 0, 0); } while (0)
; #define PG8_LDA(dst, b, h) do { _Pragma("unroll") for (int m = 0; m < 4; ++m) _Pragma("unroll") for (int k = 0; k < 2; ++k) dst[m][k] = *(const PG8_LAS bf16x8*)(lds + PG8_SA(b, h) + aoff + m * 2048 + k * 1024); } while (0)
; #define PG8_LDB(dst, b, h) do { _Pragma("unroll") for (int n = 0; n < 2; ++n) _Pragma("unroll") for (int k = 0; k < 2; ++k) dst[n][k] = *(const PG8_LAS bf16x8*)(lds + PG8_SB(b, h) + boff + n * 2048 + k * 1024); } while (0)
; #define PG8_MMA(ai, bj, At, Bt) do { __builtin_amdgcn_s_setprio(1); _Pragma("unroll") for (int m = 0; m < 4; ++m) _Pragma("unroll") for (int n = 0; n < 2; ++n) _Pragma("unroll") for (int k = 0; k < 2; ++k) \
;         acc[ai][bj][m][n] = __builtin_amdgcn_mfma_f32_16x16x32_bf16(Bt[n][k], At[m][k], acc[ai][bj][m][n], 0, 0, 0); __builtin_amdgcn_s_setprio(0); } while (0)
; #define PG8_WAIT_V(n) asm volatile("s_waitcnt vmcnt(" #n ")" ::: "memory")
; #define PG8_WAIT_L(n) asm volatile("s_waitcnt lgkmcnt(" #n ")" ::: "memory")
; #define PG8_BAR __builtin_amdgcn_s_barrier()
; #define PG8_SCHED __builtin_amdgcn_sched_barrier(0)
; template <class Epi, class Sched, bool ALIGN_EPI = false, bool SP2 = false, bool RS = false, bool BPRE = false>
; __device__ __forceinline__ void gemm_phase(PG8_LAS unsigned char* lds, const Gemm g, const Sched& S, const Epi& E, const float* rs_ss = nullptr, PG8_LAS float* rs_tab = nullptr) {
;     ...
;             PG8_LDA(At, 0, 1); PG8_STAGE(PG8_SB(0, 0), b2, voffB); PG8_STAGE(PG8_SB(0, 1), b2 + hstep, voffB); PG8_STAGE(PG8_SA(0, 0), a2, voffA);
;             PG8_WAIT_V(8); PG8_WAIT_L(0); PG8_BAR; PG8_MMA(1, 0, At, B0); PG8_MMA(1, 1, At, B1); PG8_BAR; PG8_SCHED;
;             PG8_LDB(B0, 1, 0); PG8_LDB(B1, 1, 1); PG8_SCHED; PG8_LDA(At, 1, 0); PG8_STAGE(PG8_SA(0, 1), a2 + hstep, voffA);
;             PG8_WAIT_V(8); PG8_WAIT_L(0); PG8_BAR; PG8_MMA(0, 0, At, B0); PG8_MMA(0, 1, At, B1); PG8_BAR; PG8_SCHED;
	s_setprio 1
	s_waitcnt lgkmcnt(0)
	v_mfma_f32_16x16x32_bf16 v[62:65], v[130:133], v[186:189], 0
	v_mfma_f32_16x16x32_bf16 v[58:61], v[152:155], v[186:189], 0
	v_mfma_f32_16x16x32_bf16 v[42:45], v[152:155], v[194:197], 0
	v_mfma_f32_16x16x32_bf16 v[46:49], v[130:133], v[194:197], 0
	v_mfma_f32_16x16x32_bf16 v[30:33], v[130:133], v[202:205], 0
	v_mfma_f32_16x16x32_bf16 v[26:29], v[152:155], v[202:205], 0
	v_mfma_f32_16x16x32_bf16 v[10:13], v[152:155], v[210:213], 0
	v_mfma_f32_16x16x32_bf16 v[14:17], v[130:133], v[210:213], 0
	v_mfma_f32_16x16x32_bf16 v[62:65], v[134:137], v[190:193], v[62:65]
	v_mfma_f32_16x16x32_bf16 v[58:61], v[156:159], v[190:193], v[58:61]
	v_mfma_f32_16x16x32_bf16 v[42:45], v[156:159], v[198:201], v[42:45]
	v_mfma_f32_16x16x32_bf16 v[46:49], v[134:137], v[198:201], v[46:49]
	v_mfma_f32_16x16x32_bf16 v[30:33], v[134:137], v[206:209], v[30:33]
	v_mfma_f32_16x16x32_bf16 v[26:29], v[156:159], v[206:209], v[26:29]
	v_mfma_f32_16x16x32_bf16 v[10:13], v[156:159], v[214:217], v[10:13]
	v_mfma_f32_16x16x32_bf16 v[14:17], v[134:137], v[214:217], v[14:17]
	s_setprio 0
	s_setprio 1
	v_mfma_f32_16x16x32_bf16 v[54:57], v[166:169], v[186:189], 0
	v_mfma_f32_16x16x32_bf16 v[50:53], v[174:177], v[186:189], 0
	v_mfma_f32_16x16x32_bf16 v[34:37], v[174:177], v[194:197], 0
	v_mfma_f32_16x16x32_bf16 v[38:41], v[166:169], v[194:197], 0
	v_mfma_f32_16x16x32_bf16 v[22:25], v[166:169], v[202:205], 0
	v_mfma_f32_16x16x32_bf16 v[18:21], v[174:177], v[202:205], 0
	v_mfma_f32_16x16x32_bf16 v[2:5], v[174:177], v[210:213], 0
	v_mfma_f32_16x16x32_bf16 v[6:9], v[166:169], v[210:213], 0
	v_mfma_f32_16x16x32_bf16 v[54:57], v[170:173], v[190:193], v[54:57]
	v_mfma_f32_16x16x32_bf16 v[50:53], v[182:185], v[190:193], v[50:53]
	v_mfma_f32_16x16x32_bf16 v[34:37], v[182:185], v[198:201], v[34:37]
	v_mfma_f32_16x16x32_bf16 v[38:41], v[170:173], v[198:201], v[38:41]
	v_mfma_f32_16x16x32_bf16 v[22:25], v[170:173], v[206:209], v[22:25]
	v_mfma_f32_16x16x32_bf16 v[18:21], v[182:185], v[206:209], v[18:21]
	v_mfma_f32_16x16x32_bf16 v[2:5], v[182:185], v[214:217], v[2:5]
	v_mfma_f32_16x16x32_bf16 v[6:9], v[170:173], v[214:217], v[6:9]
	s_setprio 0
	s_barrier
	s_add_i32 s90, 0, 0x18000
	v_add_u32_e32 v143, s90, v160
	s_add_i32 s91, 0, 0x1c000
	ds_read_b128 v[130:133], v143
	ds_read_b128 v[134:137], v143 offset:1024
	ds_read_b128 v[152:155], v143 offset:2048
	ds_read_b128 v[156:159], v143 offset:3072
	v_add_u32_e32 v143, s91, v160
	ds_read_b128 v[166:169], v143
	ds_read_b128 v[170:173], v143 offset:1024
	ds_read_b128 v[174:177], v143 offset:2048
	ds_read_b128 v[182:185], v143 offset:3072
	s_add_u32 s70, s70, 0x80000
	s_addc_u32 s71, s71, 0
	s_mov_b32 m0, s74
	v_lshl_add_u64 v[178:179], s[70:71], 0, v[138:139]
	ds_read_b128 v[186:189], v163 offset:32768
	ds_read_b128 v[190:193], v163 offset:33792
	ds_read_b128 v[194:197], v163 offset:34816
	ds_read_b128 v[198:201], v163 offset:35840
	ds_read_b128 v[202:205], v163 offset:36864
	ds_read_b128 v[206:209], v163 offset:37888
	ds_read_b128 v[210:213], v163 offset:38912
	ds_read_b128 v[214:217], v163 offset:39936
	global_load_lds_dwordx4 v[178:179], off
	v_lshl_add_u64 v[178:179], s[70:71], 0, v[140:141]
	s_mov_b32 m0, s75
	s_nop 0
	global_load_lds_dwordx4 v[178:179], off
	s_waitcnt vmcnt(8)
	s_waitcnt lgkmcnt(0)
	s_barrier
	s_setprio 1
	s_waitcnt lgkmcnt(0)
	v_mfma_f32_16x16x32_bf16 v[126:129], v[130:133], v[186:189], v[126:129]
	v_mfma_f32_16x16x32_bf16 v[122:125], v[152:155], v[186:189], v[122:125]
	v_mfma_f32_16x16x32_bf16 v[106:109], v[152:155], v[194:197], v[106:109]
	v_mfma_f32_16x16x32_bf16 v[110:113], v[130:133], v[194:197], v[110:113]
	v_mfma_f32_16x16x32_bf16 v[94:97], v[130:133], v[202:205], v[94:97]
	v_mfma_f32_16x16x32_bf16 v[90:93], v[152:155], v[202:205], v[90:93]
	v_mfma_f32_16x16x32_bf16 v[74:77], v[152:155], v[210:213], v[74:77]
	v_mfma_f32_16x16x32_bf16 v[78:81], v[130:133], v[210:213], v[78:81]
	v_mfma_f32_16x16x32_bf16 v[126:129], v[134:137], v[190:193], v[126:129]
	v_mfma_f32_16x16x32_bf16 v[122:125], v[156:159], v[190:193], v[122:125]
	v_mfma_f32_16x16x32_bf16 v[106:109], v[156:159], v[198:201], v[106:109]
	v_mfma_f32_16x16x32_bf16 v[110:113], v[134:137], v[198:201], v[110:113]
	v_mfma_f32_16x16x32_bf16 v[94:97], v[134:137], v[206:209], v[94:97]
	v_mfma_f32_16x16x32_bf16 v[90:93], v[156:159], v[206:209], v[90:93]
	v_mfma_f32_16x16x32_bf16 v[74:77], v[156:159], v[214:217], v[74:77]
	v_mfma_f32_16x16x32_bf16 v[78:81], v[134:137], v[214:217], v[78:81]
	s_setprio 0
	s_setprio 1
	v_mfma_f32_16x16x32_bf16 v[118:121], v[166:169], v[186:189], v[118:121]
	v_mfma_f32_16x16x32_bf16 v[114:117], v[174:177], v[186:189], v[114:117]
	v_mfma_f32_16x16x32_bf16 v[98:101], v[174:177], v[194:197], v[98:101]
	v_mfma_f32_16x16x32_bf16 v[102:105], v[166:169], v[194:197], v[102:105]
	v_mfma_f32_16x16x32_bf16 v[86:89], v[166:169], v[202:205], v[86:89]
	v_mfma_f32_16x16x32_bf16 v[82:85], v[174:177], v[202:205], v[82:85]
	v_mfma_f32_16x16x32_bf16 v[66:69], v[174:177], v[210:213], v[66:69]
	v_mfma_f32_16x16x32_bf16 v[70:73], v[166:169], v[210:213], v[70:73]
	v_mfma_f32_16x16x32_bf16 v[118:121], v[170:173], v[190:193], v[118:121]
	v_mfma_f32_16x16x32_bf16 v[114:117], v[182:185], v[190:193], v[114:117]
	v_mfma_f32_16x16x32_bf16 v[98:101], v[182:185], v[198:201], v[98:101]
	v_mfma_f32_16x16x32_bf16 v[102:105], v[170:173], v[198:201], v[102:105]
	v_mfma_f32_16x16x32_bf16 v[86:89], v[170:173], v[206:209], v[86:89]
	v_mfma_f32_16x16x32_bf16 v[82:85], v[182:185], v[206:209], v[82:85]
	v_mfma_f32_16x16x32_bf16 v[66:69], v[182:185], v[214:217], v[66:69]
	v_mfma_f32_16x16x32_bf16 v[70:73], v[170:173], v[214:217], v[70:73]
	s_setprio 0
	s_barrier
; #define PG8_STAGE(bufoff, gbase, voff) do { _Pragma("unroll") for (int _i = 0; _i < 2; ++_i) \
;         __builtin_amdgcn_global_load_lds((const unsigned*)((const char*)(gbase) + (voff)[_i]), (PG8_LAS unsigned*)(lds + (bufoff) + ldsw + _i * 8192), 16, 0, 0); } while (0)
; #define PG8_LDA(dst, b, h) do { _Pragma("unroll") for (int m = 0; m < 4; ++m) _Pragma("unroll") for (int k = 0; k < 2; ++k) dst[m][k] = *(const PG8_LAS bf16x8*)(lds + PG8_SA(b, h) + aoff + m * 2048 + k * 1024); } while (0)
; #define PG8_LDB(dst, b, h) do { _Pragma("unroll") for (int n = 0; n < 2; ++n) _Pragma("unroll") for (int k = 0; k < 2; ++k) dst[n][k] = *(const PG8_LAS bf16x8*)(lds + PG8_SB(b, h) + boff + n * 2048 + k * 1024); } while (0)
; #define PG8_WAIT_V(n) asm volatile("s_waitcnt vmcnt(" #n ")" ::: "memory")
; #define PG8_WAIT_L(n) asm volatile("s_waitcnt lgkmcnt(" #n ")" ::: "memory")
; #define PG8_BAR __builtin_amdgcn_s_barrier()
; #define PG8_SCHED __builtin_amdgcn_sched_barrier(0)
; template <class Epi, class Sched, bool ALIGN_EPI = false, bool SP2 = false, bool RS = false, bool BPRE = false>
; __device__ __forceinline__ void gemm_phase(PG8_LAS unsigned char* lds, const Gemm g, const Sched& S, const Epi& E, const float* rs_ss = nullptr, PG8_LAS float* rs_tab = nullptr) {
;     ...
;             PG8_LDB(B0, 0, 0); PG8_LDB(B1, 0, 1); PG8_SCHED; PG8_LDA(At, 0, 0); PG8_STAGE(PG8_SA(1, 1), a1 + hstep, voffA);
;             PG8_WAIT_V(8); PG8_WAIT_L(0); PG8_BAR; PG8_MMA(0, 0, At, B0); PG8_MMA(0, 1, At, B1); PG8_BAR; PG8_SCHED;
;             PG8_LDA(At, 0, 1); PG8_STAGE(PG8_SB(0, 0), b2, voffB); PG8_STAGE(PG8_SB(0, 1), b2 + hstep, voffB); PG8_STAGE(PG8_SA(0, 0), a2, voffA);
;             PG8_WAIT_V(8); PG8_WAIT_L(0); PG8_BAR; PG8_MMA(1, 0, At, B0); PG8_MMA(1, 1, At, B1); PG8_BAR; PG8_SCHED;
;             PG8_LDB(B0, 1, 0); PG8_LDB(B1, 1, 1); PG8_SCHED; PG8_LDA(At, 1, 0); PG8_STAGE(PG8_SA(0, 1), a2 + hstep, voffA);
;             PG8_WAIT_V(8); PG8_WAIT_L(0); PG8_BAR; PG8_MMA(0, 0, At, B0); PG8_MMA(0, 1, At, B1); PG8_BAR; PG8_SCHED;
;             PG8_LDA(At, 1, 1); PG8_STAGE(PG8_SB(1, 0), b3, voffB); PG8_STAGE(PG8_SB(1, 1), b3 + hstep, voffB); PG8_STAGE(PG8_SA(1, 0), a3, voffA);
;             PG8_WAIT_V(8); PG8_WAIT_L(0); PG8_BAR; PG8_MMA(1, 0, At, B0); PG8_MMA(1, 1, At, B1); PG8_BAR; PG8_SCHED;
	s_add_u32 s70, s60, 0x4000
	s_addc_u32 s71, s61, 0
	s_add_i32 s90, s90, s15
	v_lshl_add_u64 v[178:179], s[70:71], 0, v[138:139]
	s_mov_b32 m0, s90
	ds_read_b128 v[186:189], v163 offset:49152
	ds_read_b128 v[190:193], v163 offset:50176
	ds_read_b128 v[194:197], v163 offset:51200
	ds_read_b128 v[198:201], v163 offset:52224
	ds_read_b128 v[202:205], v163 offset:53248
	ds_read_b128 v[206:209], v163 offset:54272
	ds_read_b128 v[210:213], v163 offset:55296
	ds_read_b128 v[214:217], v163 offset:56320
	global_load_lds_dwordx4 v[178:179], off
	s_add_i32 m0, s90, 0x2000
	s_add_u32 s60, s60, 0x84000
	v_lshl_add_u64 v[178:179], s[70:71], 0, v[140:141]
	s_addc_u32 s61, s61, 0
	s_add_i32 s70, s91, s15
	global_load_lds_dwordx4 v[178:179], off
	v_lshl_add_u64 v[178:179], s[60:61], 0, v[138:139]
	s_mov_b32 m0, s70
	s_nop 0
	global_load_lds_dwordx4 v[178:179], off
	v_lshl_add_u64 v[178:179], s[60:61], 0, v[140:141]
	s_add_i32 m0, s70, 0x2000
	s_nop 0
	global_load_lds_dwordx4 v[178:179], off
	v_lshl_add_u64 v[178:179], s[58:59], 0, v[138:139]
	s_mov_b32 m0, s79
	s_nop 0
	global_load_lds_dwordx4 v[178:179], off
	v_lshl_add_u64 v[178:179], s[58:59], 0, v[140:141]
	s_mov_b32 m0, s80
	s_nop 0
	global_load_lds_dwordx4 v[178:179], off
	s_waitcnt vmcnt(8)
	s_waitcnt lgkmcnt(0)
	s_barrier
	s_setprio 1
	s_waitcnt lgkmcnt(0)
	v_mfma_f32_16x16x32_bf16 v[62:65], v[130:133], v[186:189], v[62:65]
	v_mfma_f32_16x16x32_bf16 v[58:61], v[152:155], v[186:189], v[58:61]
	v_mfma_f32_16x16x32_bf16 v[42:45], v[152:155], v[194:197], v[42:45]
	v_mfma_f32_16x16x32_bf16 v[46:49], v[130:133], v[194:197], v[46:49]
	v_mfma_f32_16x16x32_bf16 v[30:33], v[130:133], v[202:205], v[30:33]
	v_mfma_f32_16x16x32_bf16 v[26:29], v[152:155], v[202:205], v[26:29]
	v_mfma_f32_16x16x32_bf16 v[10:13], v[152:155], v[210:213], v[10:13]
	v_mfma_f32_16x16x32_bf16 v[14:17], v[130:133], v[210:213], v[14:17]
	v_mfma_f32_16x16x32_bf16 v[62:65], v[134:137], v[190:193], v[62:65]
	v_mfma_f32_16x16x32_bf16 v[58:61], v[156:159], v[190:193], v[58:61]
	v_mfma_f32_16x16x32_bf16 v[42:45], v[156:159], v[198:201], v[42:45]
	v_mfma_f32_16x16x32_bf16 v[46:49], v[134:137], v[198:201], v[46:49]
	v_mfma_f32_16x16x32_bf16 v[30:33], v[134:137], v[206:209], v[30:33]
	v_mfma_f32_16x16x32_bf16 v[26:29], v[156:159], v[206:209], v[26:29]
	v_mfma_f32_16x16x32_bf16 v[10:13], v[156:159], v[214:217], v[10:13]
	v_mfma_f32_16x16x32_bf16 v[14:17], v[134:137], v[214:217], v[14:17]
	s_setprio 0
	s_setprio 1
	v_mfma_f32_16x16x32_bf16 v[54:57], v[166:169], v[186:189], v[54:57]
	v_mfma_f32_16x16x32_bf16 v[50:53], v[174:177], v[186:189], v[50:53]
	v_mfma_f32_16x16x32_bf16 v[34:37], v[174:177], v[194:197], v[34:37]
	v_mfma_f32_16x16x32_bf16 v[38:41], v[166:169], v[194:197], v[38:41]
	v_mfma_f32_16x16x32_bf16 v[22:25], v[166:169], v[202:205], v[22:25]
	v_mfma_f32_16x16x32_bf16 v[18:21], v[174:177], v[202:205], v[18:21]
	v_mfma_f32_16x16x32_bf16 v[2:5], v[174:177], v[210:213], v[2:5]
	v_mfma_f32_16x16x32_bf16 v[6:9], v[166:169], v[210:213], v[6:9]
	v_mfma_f32_16x16x32_bf16 v[54:57], v[170:173], v[190:193], v[54:57]
	v_mfma_f32_16x16x32_bf16 v[50:53], v[182:185], v[190:193], v[50:53]
	v_mfma_f32_16x16x32_bf16 v[34:37], v[182:185], v[198:201], v[34:37]
	v_mfma_f32_16x16x32_bf16 v[38:41], v[170:173], v[198:201], v[38:41]
	v_mfma_f32_16x16x32_bf16 v[22:25], v[170:173], v[206:209], v[22:25]
	v_mfma_f32_16x16x32_bf16 v[18:21], v[182:185], v[206:209], v[18:21]
	v_mfma_f32_16x16x32_bf16 v[2:5], v[182:185], v[214:217], v[2:5]
	v_mfma_f32_16x16x32_bf16 v[6:9], v[170:173], v[214:217], v[6:9]
	s_setprio 0
	s_barrier
	s_add_i32 s89, s89, 2
	s_add_u32 s56, s56, 0x8000
	s_addc_u32 s57, s57, 0
	s_add_u32 s87, s87, 0x8000
	s_addc_u32 s88, s88, 0
.LBB0_196:
	ds_read_b128 v[130:133], v161
	ds_read_b128 v[134:137], v161 offset:1024
	ds_read_b128 v[152:155], v161 offset:2048
	ds_read_b128 v[156:159], v161 offset:3072
	ds_read_b128 v[166:169], v162
	ds_read_b128 v[170:173], v162 offset:1024
	ds_read_b128 v[174:177], v162 offset:2048
	ds_read_b128 v[182:185], v162 offset:3072
	s_add_u32 s58, s56, 0xfff84000
	s_addc_u32 s59, s57, -1
	s_cmp_eq_u32 s89, 28
	s_cselect_b32 s70, s19, s58
	s_cselect_b32 s71, s5, s59
	s_cselect_b32 s60, s47, s87
	s_cselect_b32 s61, s17, s88
	s_add_u32 s58, s70, 0x4000
	s_addc_u32 s59, s71, 0
	v_lshl_add_u64 v[178:179], s[56:57], 0, v[138:139]
	s_add_i32 m0, s72, 0xc000
	ds_read_b128 v[186:189], v163
	ds_read_b128 v[190:193], v163 offset:1024
	ds_read_b128 v[194:197], v163 offset:2048
	ds_read_b128 v[198:201], v163 offset:3072
	ds_read_b128 v[202:205], v163 offset:4096
	ds_read_b128 v[206:209], v163 offset:5120
	ds_read_b128 v[210:213], v163 offset:6144
	ds_read_b128 v[214:217], v163 offset:7168
	global_load_lds_dwordx4 v[178:179], off
	v_lshl_add_u64 v[178:179], s[56:57], 0, v[146:147]
	s_add_i32 m0, s72, 0xe000
	s_nop 0
	global_load_lds_dwordx4 v[178:179], off
	s_waitcnt vmcnt(8)
	s_waitcnt lgkmcnt(0)
	s_barrier
; #define PG8_STAGE(bufoff, gbase, voff) do { _Pragma("unroll") for (int _i = 0; _i < 2; ++_i) \
;         __builtin_amdgcn_global_load_lds((const unsigned*)((const char*)(gbase) + (voff)[_i]), (PG8_LAS unsigned*)(lds + (bufoff) + ldsw + _i * 8192), 16, 0, 0); } while (0)
; #define PG8_LDA(dst, b, h) do { _Pragma("unroll") for (int m = 0; m < 4; ++m) _Pragma("unroll") for (int k = 0; k < 2; ++k) dst[m][k] = *(const PG8_LAS bf16x8*)(lds + PG8_SA(b, h) + aoff + m * 2048 + k * 1024); } while (0)
; #define PG8_MMA(ai, bj, At, Bt) do { __builtin_amdgcn_s_setprio(1); _Pragma("unroll") for (int m = 0; m < 4; ++m) _Pragma("unroll") for (int n = 0; n < 2; ++n) _Pragma("unroll") for (int k = 0; k < 2; ++k) \
;         acc[ai][bj][m][n] = __builtin_amdgcn_mfma_f32_16x16x32_bf16(Bt[n][k], At[m][k], acc[ai][bj][m][n], 0, 0, 0); __builtin_amdgcn_s_setprio(0); } while (0)
; #define PG8_WAIT_V(n) asm volatile("s_waitcnt vmcnt(" #n ")" ::: "memory")
; #define PG8_WAIT_L(n) asm volatile("s_waitcnt lgkmcnt(" #n ")" ::: "memory")
; #define PG8_BAR __builtin_amdgcn_s_barrier()
; #define PG8_SCHED __builtin_amdgcn_sched_barrier(0)
; template <class Epi, class Sched, bool ALIGN_EPI = false, bool SP2 = false, bool RS = false, bool BPRE = false>
; __device__ __forceinline__ void gemm_phase(PG8_LAS unsigned char* lds, const Gemm g, const Sched& S, const Epi& E, const float* rs_ss = nullptr, PG8_LAS float* rs_tab = nullptr) {
;     ...
;             PG8_WAIT_V(8); PG8_WAIT_L(0); PG8_BAR; PG8_MMA(0, 0, At, B0); PG8_MMA(0, 1, At, B1); PG8_BAR; PG8_SCHED;
;             PG8_LDA(At, 0, 1); PG8_STAGE(PG8_SB(0, 0), b2, voffB); PG8_STAGE(PG8_SB(0, 1), b2 + hstep, voffB); PG8_STAGE(PG8_SA(0, 0), a2, voffA);
;             PG8_WAIT_V(8); PG8_WAIT_L(0); PG8_BAR; PG8_MMA(1, 0, At, B0); PG8_MMA(1, 1, At, B1); PG8_BAR; PG8_SCHED;
	s_setprio 1
	s_waitcnt lgkmcnt(0)
	v_mfma_f32_16x16x32_bf16 v[126:129], v[130:133], v[186:189], v[126:129]
	v_mfma_f32_16x16x32_bf16 v[122:125], v[152:155], v[186:189], v[122:125]
	v_mfma_f32_16x16x32_bf16 v[106:109], v[152:155], v[194:197], v[106:109]
	v_mfma_f32_16x16x32_bf16 v[110:113], v[130:133], v[194:197], v[110:113]
	v_mfma_f32_16x16x32_bf16 v[94:97], v[130:133], v[202:205], v[94:97]
	v_mfma_f32_16x16x32_bf16 v[90:93], v[152:155], v[202:205], v[90:93]
	v_mfma_f32_16x16x32_bf16 v[74:77], v[152:155], v[210:213], v[74:77]
	v_mfma_f32_16x16x32_bf16 v[78:81], v[130:133], v[210:213], v[78:81]
	v_mfma_f32_16x16x32_bf16 v[126:129], v[134:137], v[190:193], v[126:129]
	v_mfma_f32_16x16x32_bf16 v[122:125], v[156:159], v[190:193], v[122:125]
	v_mfma_f32_16x16x32_bf16 v[106:109], v[156:159], v[198:201], v[106:109]
	v_mfma_f32_16x16x32_bf16 v[110:113], v[134:137], v[198:201], v[110:113]
	v_mfma_f32_16x16x32_bf16 v[94:97], v[134:137], v[206:209], v[94:97]
	v_mfma_f32_16x16x32_bf16 v[90:93], v[156:159], v[206:209], v[90:93]
	v_mfma_f32_16x16x32_bf16 v[74:77], v[156:159], v[214:217], v[74:77]
	v_mfma_f32_16x16x32_bf16 v[78:81], v[134:137], v[214:217], v[78:81]
	s_setprio 0
	s_setprio 1
	v_mfma_f32_16x16x32_bf16 v[118:121], v[166:169], v[186:189], v[118:121]
	v_mfma_f32_16x16x32_bf16 v[114:117], v[174:177], v[186:189], v[114:117]
	v_mfma_f32_16x16x32_bf16 v[98:101], v[174:177], v[194:197], v[98:101]
	v_mfma_f32_16x16x32_bf16 v[102:105], v[166:169], v[194:197], v[102:105]
	v_mfma_f32_16x16x32_bf16 v[86:89], v[166:169], v[202:205], v[86:89]
	v_mfma_f32_16x16x32_bf16 v[82:85], v[174:177], v[202:205], v[82:85]
	v_mfma_f32_16x16x32_bf16 v[66:69], v[174:177], v[210:213], v[66:69]
	v_mfma_f32_16x16x32_bf16 v[70:73], v[166:169], v[210:213], v[70:73]
	v_mfma_f32_16x16x32_bf16 v[118:121], v[170:173], v[190:193], v[118:121]
	v_mfma_f32_16x16x32_bf16 v[114:117], v[182:185], v[190:193], v[114:117]
	v_mfma_f32_16x16x32_bf16 v[98:101], v[182:185], v[198:201], v[98:101]
	v_mfma_f32_16x16x32_bf16 v[102:105], v[170:173], v[198:201], v[102:105]
	v_mfma_f32_16x16x32_bf16 v[86:89], v[170:173], v[206:209], v[86:89]
	v_mfma_f32_16x16x32_bf16 v[82:85], v[182:185], v[206:209], v[82:85]
	v_mfma_f32_16x16x32_bf16 v[66:69], v[182:185], v[214:217], v[66:69]
	v_mfma_f32_16x16x32_bf16 v[70:73], v[170:173], v[214:217], v[70:73]
	s_setprio 0
	s_barrier
	s_add_i32 s90, s83, s15
	v_lshl_add_u64 v[178:179], s[60:61], 0, v[138:139]
	s_mov_b32 m0, s90
	ds_read_b128 v[186:189], v163 offset:16384
	ds_read_b128 v[190:193], v163 offset:17408
	ds_read_b128 v[194:197], v163 offset:18432
	ds_read_b128 v[198:201], v163 offset:19456
	ds_read_b128 v[202:205], v163 offset:20480
	ds_read_b128 v[206:209], v163 offset:21504
	ds_read_b128 v[210:213], v163 offset:22528
	ds_read_b128 v[214:217], v163 offset:23552
	global_load_lds_dwordx4 v[178:179], off
	s_add_i32 m0, s90, 0x2000
	s_add_u32 s90, s60, 0x80000
	v_lshl_add_u64 v[178:179], s[60:61], 0, v[140:141]
	s_addc_u32 s91, s61, 0
	s_add_i32 s92, s86, s15
	global_load_lds_dwordx4 v[178:179], off
	v_lshl_add_u64 v[178:179], s[90:91], 0, v[138:139]
	s_mov_b32 m0, s92
	s_nop 0
	global_load_lds_dwordx4 v[178:179], off
	v_lshl_add_u64 v[178:179], s[90:91], 0, v[140:141]
	s_add_i32 m0, s92, 0x2000
	s_nop 0
	global_load_lds_dwordx4 v[178:179], off
	v_lshl_add_u64 v[178:179], s[70:71], 0, v[138:139]
	s_mov_b32 m0, s72
	s_nop 0
	global_load_lds_dwordx4 v[178:179], off
	v_lshl_add_u64 v[178:179], s[70:71], 0, v[140:141]
	s_mov_b32 m0, s73
	s_nop 0
	global_load_lds_dwordx4 v[178:179], off
	s_waitcnt vmcnt(8)
	s_waitcnt lgkmcnt(0)
	s_barrier
	s_setprio 1
	s_waitcnt lgkmcnt(0)
	v_mfma_f32_16x16x32_bf16 v[62:65], v[130:133], v[186:189], v[62:65]
	v_mfma_f32_16x16x32_bf16 v[58:61], v[152:155], v[186:189], v[58:61]
	v_mfma_f32_16x16x32_bf16 v[42:45], v[152:155], v[194:197], v[42:45]
	v_mfma_f32_16x16x32_bf16 v[46:49], v[130:133], v[194:197], v[46:49]
	v_mfma_f32_16x16x32_bf16 v[30:33], v[130:133], v[202:205], v[30:33]
	v_mfma_f32_16x16x32_bf16 v[26:29], v[152:155], v[202:205], v[26:29]
	v_mfma_f32_16x16x32_bf16 v[10:13], v[152:155], v[210:213], v[10:13]
	v_mfma_f32_16x16x32_bf16 v[14:17], v[130:133], v[210:213], v[14:17]
	v_mfma_f32_16x16x32_bf16 v[62:65], v[134:137], v[190:193], v[62:65]
	v_mfma_f32_16x16x32_bf16 v[58:61], v[156:159], v[190:193], v[58:61]
	v_mfma_f32_16x16x32_bf16 v[42:45], v[156:159], v[198:201], v[42:45]
	v_mfma_f32_16x16x32_bf16 v[46:49], v[134:137], v[198:201], v[46:49]
	v_mfma_f32_16x16x32_bf16 v[30:33], v[134:137], v[206:209], v[30:33]
	v_mfma_f32_16x16x32_bf16 v[26:29], v[156:159], v[206:209], v[26:29]
	v_mfma_f32_16x16x32_bf16 v[10:13], v[156:159], v[214:217], v[10:13]
	v_mfma_f32_16x16x32_bf16 v[14:17], v[134:137], v[214:217], v[14:17]
	s_setprio 0
	s_setprio 1
	v_mfma_f32_16x16x32_bf16 v[54:57], v[166:169], v[186:189], v[54:57]
	v_mfma_f32_16x16x32_bf16 v[50:53], v[174:177], v[186:189], v[50:53]
	v_mfma_f32_16x16x32_bf16 v[34:37], v[174:177], v[194:197], v[34:37]
	v_mfma_f32_16x16x32_bf16 v[38:41], v[166:169], v[194:197], v[38:41]
	v_mfma_f32_16x16x32_bf16 v[22:25], v[166:169], v[202:205], v[22:25]
	v_mfma_f32_16x16x32_bf16 v[18:21], v[174:177], v[202:205], v[18:21]
	v_mfma_f32_16x16x32_bf16 v[2:5], v[174:177], v[210:213], v[2:5]
	v_mfma_f32_16x16x32_bf16 v[6:9], v[166:169], v[210:213], v[6:9]
	v_mfma_f32_16x16x32_bf16 v[54:57], v[170:173], v[190:193], v[54:57]
	v_mfma_f32_16x16x32_bf16 v[50:53], v[182:185], v[190:193], v[50:53]
	v_mfma_f32_16x16x32_bf16 v[34:37], v[182:185], v[198:201], v[34:37]
	v_mfma_f32_16x16x32_bf16 v[38:41], v[170:173], v[198:201], v[38:41]
	v_mfma_f32_16x16x32_bf16 v[22:25], v[170:173], v[206:209], v[22:25]
	v_mfma_f32_16x16x32_bf16 v[18:21], v[182:185], v[206:209], v[18:21]
	v_mfma_f32_16x16x32_bf16 v[2:5], v[182:185], v[214:217], v[2:5]
	v_mfma_f32_16x16x32_bf16 v[6:9], v[170:173], v[214:217], v[6:9]
	s_setprio 0
	s_barrier
; #define PG8_STAGE(bufoff, gbase, voff) do { _Pragma("unroll") for (int _i = 0; _i < 2; ++_i) \
;         __builtin_amdgcn_global_load_lds((const unsigned*)((const char*)(gbase) + (voff)[_i]), (PG8_LAS unsigned*)(lds + (bufoff) + ldsw + _i * 8192), 16, 0, 0); } while (0)
; #define PG8_LDA(dst, b, h) do { _Pragma("unroll") for (int m = 0; m < 4; ++m) _Pragma("unroll") for (int k = 0; k < 2; ++k) dst[m][k] = *(const PG8_LAS bf16x8*)(lds + PG8_SA(b, h) + aoff + m * 2048 + k * 1024); } while (0)
; #define PG8_LDB(dst, b, h) do { _Pragma("unroll") for (int n = 0; n < 2; ++n) _Pragma("unroll") for (int k = 0; k < 2; ++k) dst[n][k] = *(const PG8_LAS bf16x8*)(lds + PG8_SB(b, h) + boff + n * 2048 + k * 1024); } while (0)
; #define PG8_MMA(ai, bj, At, Bt) do { __builtin_amdgcn_s_setprio(1); _Pragma("unroll") for (int m = 0; m < 4; ++m) _Pragma("unroll") for (int n = 0; n < 2; ++n) _Pragma("unroll") for (int k = 0; k < 2; ++k) \
;         acc[ai][bj][m][n] = __builtin_amdgcn_mfma_f32_16x16x32_bf16(Bt[n][k], At[m][k], acc[ai][bj][m][n], 0, 0, 0); __builtin_amdgcn_s_setprio(0); } while (0)
; #define PG8_WAIT_V(n) asm volatile("s_waitcnt vmcnt(" #n ")" ::: "memory")
; #define PG8_WAIT_L(n) asm volatile("s_waitcnt lgkmcnt(" #n ")" ::: "memory")
; #define PG8_BAR __builtin_amdgcn_s_barrier()
; #define PG8_SCHED __builtin_amdgcn_sched_barrier(0)
; template <class Epi, class Sched, bool ALIGN_EPI = false, bool SP2 = false, bool RS = false, bool BPRE = false>
; __device__ __forceinline__ void gemm_phase(PG8_LAS unsigned char* lds, const Gemm g, const Sched& S, const Epi& E, const float* rs_ss = nullptr, PG8_LAS float* rs_tab = nullptr) {
;     ...
;             PG8_LDB(B0, 1, 0); PG8_LDB(B1, 1, 1); PG8_SCHED; PG8_LDA(At, 1, 0); PG8_STAGE(PG8_SA(0, 1), a2 + hstep, voffA);
;             PG8_WAIT_V(8); PG8_WAIT_L(0); PG8_BAR; PG8_MMA(0, 0, At, B0); PG8_MMA(0, 1, At, B1); PG8_BAR; PG8_SCHED;
	s_add_i32 s90, 0, 0x18000
	v_add_u32_e32 v143, s90, v160
	s_add_i32 s91, 0, 0x1c000
	ds_read_b128 v[130:133], v143
	ds_read_b128 v[134:137], v143 offset:1024
	ds_read_b128 v[152:155], v143 offset:2048
	ds_read_b128 v[156:159], v143 offset:3072
	v_add_u32_e32 v143, s91, v160
	ds_read_b128 v[166:169], v143
	ds_read_b128 v[170:173], v143 offset:1024
	ds_read_b128 v[174:177], v143 offset:2048
	ds_read_b128 v[182:185], v143 offset:3072
	s_add_u32 s70, s70, 0x80000
	s_addc_u32 s71, s71, 0
	s_mov_b32 m0, s74
	v_lshl_add_u64 v[178:179], s[70:71], 0, v[138:139]
	ds_read_b128 v[186:189], v163 offset:32768
	ds_read_b128 v[190:193], v163 offset:33792
	ds_read_b128 v[194:197], v163 offset:34816
	ds_read_b128 v[198:201], v163 offset:35840
	ds_read_b128 v[202:205], v163 offset:36864
	ds_read_b128 v[206:209], v163 offset:37888
	ds_read_b128 v[210:213], v163 offset:38912
	ds_read_b128 v[214:217], v163 offset:39936
	global_load_lds_dwordx4 v[178:179], off
	v_lshl_add_u64 v[178:179], s[70:71], 0, v[140:141]
	s_mov_b32 m0, s75
	s_nop 0
	global_load_lds_dwordx4 v[178:179], off
	s_waitcnt vmcnt(8)
	s_waitcnt lgkmcnt(0)
	s_barrier
	s_setprio 1
	s_waitcnt lgkmcnt(0)
	v_mfma_f32_16x16x32_bf16 v[126:129], v[130:133], v[186:189], v[126:129]
	v_mfma_f32_16x16x32_bf16 v[122:125], v[152:155], v[186:189], v[122:125]
	v_mfma_f32_16x16x32_bf16 v[106:109], v[152:155], v[194:197], v[106:109]
	v_mfma_f32_16x16x32_bf16 v[110:113], v[130:133], v[194:197], v[110:113]
	v_mfma_f32_16x16x32_bf16 v[94:97], v[130:133], v[202:205], v[94:97]
	v_mfma_f32_16x16x32_bf16 v[90:93], v[152:155], v[202:205], v[90:93]
	v_mfma_f32_16x16x32_bf16 v[74:77], v[152:155], v[210:213], v[74:77]
	v_mfma_f32_16x16x32_bf16 v[78:81], v[130:133], v[210:213], v[78:81]
	v_mfma_f32_16x16x32_bf16 v[126:129], v[134:137], v[190:193], v[126:129]
	v_mfma_f32_16x16x32_bf16 v[122:125], v[156:159], v[190:193], v[122:125]
	v_mfma_f32_16x16x32_bf16 v[106:109], v[156:159], v[198:201], v[106:109]
	v_mfma_f32_16x16x32_bf16 v[110:113], v[134:137], v[198:201], v[110:113]
	v_mfma_f32_16x16x32_bf16 v[94:97], v[134:137], v[206:209], v[94:97]
	v_mfma_f32_16x16x32_bf16 v[90:93], v[156:159], v[206:209], v[90:93]
	v_mfma_f32_16x16x32_bf16 v[74:77], v[156:159], v[214:217], v[74:77]
	v_mfma_f32_16x16x32_bf16 v[78:81], v[134:137], v[214:217], v[78:81]
	s_setprio 0
	s_setprio 1
	v_mfma_f32_16x16x32_bf16 v[118:121], v[166:169], v[186:189], v[118:121]
	v_mfma_f32_16x16x32_bf16 v[114:117], v[174:177], v[186:189], v[114:117]
	v_mfma_f32_16x16x32_bf16 v[98:101], v[174:177], v[194:197], v[98:101]
	v_mfma_f32_16x16x32_bf16 v[102:105], v[166:169], v[194:197], v[102:105]
	v_mfma_f32_16x16x32_bf16 v[86:89], v[166:169], v[202:205], v[86:89]
	v_mfma_f32_16x16x32_bf16 v[82:85], v[174:177], v[202:205], v[82:85]
	v_mfma_f32_16x16x32_bf16 v[66:69], v[174:177], v[210:213], v[66:69]
	v_mfma_f32_16x16x32_bf16 v[70:73], v[166:169], v[210:213], v[70:73]
	v_mfma_f32_16x16x32_bf16 v[118:121], v[170:173], v[190:193], v[118:121]
	v_mfma_f32_16x16x32_bf16 v[114:117], v[182:185], v[190:193], v[114:117]
	v_mfma_f32_16x16x32_bf16 v[98:101], v[182:185], v[198:201], v[98:101]
	v_mfma_f32_16x16x32_bf16 v[102:105], v[170:173], v[198:201], v[102:105]
	v_mfma_f32_16x16x32_bf16 v[86:89], v[170:173], v[206:209], v[86:89]
	v_mfma_f32_16x16x32_bf16 v[82:85], v[182:185], v[206:209], v[82:85]
	v_mfma_f32_16x16x32_bf16 v[66:69], v[182:185], v[214:217], v[66:69]
	v_mfma_f32_16x16x32_bf16 v[70:73], v[170:173], v[214:217], v[70:73]
	s_setprio 0
	s_barrier
; #define PG8_STAGE(bufoff, gbase, voff) do { _Pragma("unroll") for (int _i = 0; _i < 2; ++_i) \
;         __builtin_amdgcn_global_load_lds((const unsigned*)((const char*)(gbase) + (voff)[_i]), (PG8_LAS unsigned*)(lds + (bufoff) + ldsw + _i * 8192), 16, 0, 0); } while (0)
; #define PG8_LDA(dst, b, h) do { _Pragma("unroll") for (int m = 0; m < 4; ++m) _Pragma("unroll") for (int k = 0; k < 2; ++k) dst[m][k] = *(const PG8_LAS bf16x8*)(lds + PG8_SA(b, h) + aoff + m * 2048 + k * 1024); } while (0)
; #define PG8_MMA(ai, bj, At, Bt) do { __builtin_amdgcn_s_setprio(1); _Pragma("unroll") for (int m = 0; m < 4; ++m) _Pragma("unroll") for (int n = 0; n < 2; ++n) _Pragma("unroll") for (int k = 0; k < 2; ++k) \
;         acc[ai][bj][m][n] = __builtin_amdgcn_mfma_f32_16x16x32_bf16(Bt[n][k], At[m][k], acc[ai][bj][m][n], 0, 0, 0); __builtin_amdgcn_s_setprio(0); } while (0)
; #define PG8_WAIT_V(n) asm volatile("s_waitcnt vmcnt(" #n ")" ::: "memory")
; #define PG8_WAIT_L(n) asm volatile("s_waitcnt lgkmcnt(" #n ")" ::: "memory")
; #define PG8_BAR __builtin_amdgcn_s_barrier()
; #define PG8_SCHED __builtin_amdgcn_sched_barrier(0)
; template <class Epi, class Sched, bool ALIGN_EPI = false, bool SP2 = false, bool RS = false, bool BPRE = false>
; __device__ __forceinline__ void gemm_phase(PG8_LAS unsigned char* lds, const Gemm g, const Sched& S, const Epi& E, const float* rs_ss = nullptr, PG8_LAS float* rs_tab = nullptr) {
;     ...
;             PG8_LDA(At, 1, 1); PG8_STAGE(PG8_SB(1, 0), b3, voffB); PG8_STAGE(PG8_SB(1, 1), b3 + hstep, voffB); PG8_STAGE(PG8_SA(1, 0), a3, voffA);
;             PG8_WAIT_V(8); PG8_WAIT_L(0); PG8_BAR; PG8_MMA(1, 0, At, B0); PG8_MMA(1, 1, At, B1); PG8_BAR; PG8_SCHED;
;     ...
;         }
;         if constexpr (ALIGN_EPI) { if (wr == 0) PG8_BAR; }
	s_add_u32 s70, s60, 0x4000
	s_addc_u32 s71, s61, 0
	s_add_i32 s90, s90, s15
	v_lshl_add_u64 v[178:179], s[70:71], 0, v[138:139]
	s_mov_b32 m0, s90
	ds_read_b128 v[186:189], v163 offset:49152
	ds_read_b128 v[190:193], v163 offset:50176
	ds_read_b128 v[194:197], v163 offset:51200
	ds_read_b128 v[198:201], v163 offset:52224
	ds_read_b128 v[202:205], v163 offset:53248
	ds_read_b128 v[206:209], v163 offset:54272
	ds_read_b128 v[210:213], v163 offset:55296
	ds_read_b128 v[214:217], v163 offset:56320
	global_load_lds_dwordx4 v[178:179], off
	s_add_i32 m0, s90, 0x2000
	s_add_u32 s60, s60, 0x84000
	v_lshl_add_u64 v[178:179], s[70:71], 0, v[140:141]
	s_addc_u32 s61, s61, 0
	s_add_i32 s70, s91, s15
	global_load_lds_dwordx4 v[178:179], off
	v_lshl_add_u64 v[178:179], s[60:61], 0, v[138:139]
	s_mov_b32 m0, s70
	s_nop 0
	global_load_lds_dwordx4 v[178:179], off
	v_lshl_add_u64 v[178:179], s[60:61], 0, v[140:141]
	s_add_i32 m0, s70, 0x2000
	s_nop 0
	global_load_lds_dwordx4 v[178:179], off
	v_lshl_add_u64 v[178:179], s[58:59], 0, v[138:139]
	s_mov_b32 m0, s79
	s_nop 0
	global_load_lds_dwordx4 v[178:179], off
	v_lshl_add_u64 v[178:179], s[58:59], 0, v[140:141]
	s_mov_b32 m0, s80
	s_nop 0
	global_load_lds_dwordx4 v[178:179], off
	s_waitcnt vmcnt(8)
	s_waitcnt lgkmcnt(0)
	s_barrier
	s_setprio 1
	s_waitcnt lgkmcnt(0)
	v_mfma_f32_16x16x32_bf16 v[62:65], v[130:133], v[186:189], v[62:65]
	v_mfma_f32_16x16x32_bf16 v[58:61], v[152:155], v[186:189], v[58:61]
	v_mfma_f32_16x16x32_bf16 v[42:45], v[152:155], v[194:197], v[42:45]
	v_mfma_f32_16x16x32_bf16 v[46:49], v[130:133], v[194:197], v[46:49]
	v_mfma_f32_16x16x32_bf16 v[30:33], v[130:133], v[202:205], v[30:33]
	v_mfma_f32_16x16x32_bf16 v[26:29], v[152:155], v[202:205], v[26:29]
	v_mfma_f32_16x16x32_bf16 v[10:13], v[152:155], v[210:213], v[10:13]
	v_mfma_f32_16x16x32_bf16 v[14:17], v[130:133], v[210:213], v[14:17]
	v_mfma_f32_16x16x32_bf16 v[62:65], v[134:137], v[190:193], v[62:65]
	v_mfma_f32_16x16x32_bf16 v[58:61], v[156:159], v[190:193], v[58:61]
	v_mfma_f32_16x16x32_bf16 v[42:45], v[156:159], v[198:201], v[42:45]
	v_mfma_f32_16x16x32_bf16 v[46:49], v[134:137], v[198:201], v[46:49]
	v_mfma_f32_16x16x32_bf16 v[30:33], v[134:137], v[206:209], v[30:33]
	v_mfma_f32_16x16x32_bf16 v[26:29], v[156:159], v[206:209], v[26:29]
	v_mfma_f32_16x16x32_bf16 v[10:13], v[156:159], v[214:217], v[10:13]
	v_mfma_f32_16x16x32_bf16 v[14:17], v[134:137], v[214:217], v[14:17]
	s_setprio 0
	s_setprio 1
	v_mfma_f32_16x16x32_bf16 v[54:57], v[166:169], v[186:189], v[54:57]
	v_mfma_f32_16x16x32_bf16 v[50:53], v[174:177], v[186:189], v[50:53]
	v_mfma_f32_16x16x32_bf16 v[34:37], v[174:177], v[194:197], v[34:37]
	v_mfma_f32_16x16x32_bf16 v[38:41], v[166:169], v[194:197], v[38:41]
	v_mfma_f32_16x16x32_bf16 v[22:25], v[166:169], v[202:205], v[22:25]
	v_mfma_f32_16x16x32_bf16 v[18:21], v[174:177], v[202:205], v[18:21]
	v_mfma_f32_16x16x32_bf16 v[2:5], v[174:177], v[210:213], v[2:5]
	v_mfma_f32_16x16x32_bf16 v[6:9], v[166:169], v[210:213], v[6:9]
	v_mfma_f32_16x16x32_bf16 v[54:57], v[170:173], v[190:193], v[54:57]
	v_mfma_f32_16x16x32_bf16 v[50:53], v[182:185], v[190:193], v[50:53]
	v_mfma_f32_16x16x32_bf16 v[34:37], v[182:185], v[198:201], v[34:37]
	v_mfma_f32_16x16x32_bf16 v[38:41], v[170:173], v[198:201], v[38:41]
	v_mfma_f32_16x16x32_bf16 v[22:25], v[170:173], v[206:209], v[22:25]
	v_mfma_f32_16x16x32_bf16 v[18:21], v[182:185], v[206:209], v[18:21]
	v_mfma_f32_16x16x32_bf16 v[2:5], v[182:185], v[214:217], v[2:5]
	v_mfma_f32_16x16x32_bf16 v[6:9], v[170:173], v[214:217], v[6:9]
	s_setprio 0
	s_barrier
	s_add_i32 s89, s89, 2
	s_add_u32 s56, s56, 0x8000
	s_addc_u32 s57, s57, 0
	s_add_u32 s87, s87, 0x8000
	s_addc_u32 s88, s88, 0
	s_cmp_gt_u32 s89, 29
	s_cbranch_scc0 .LBB0_196
	s_and_b64 vcc, exec, s[12:13]
	s_cbranch_vccz .LBB0_199
	s_barrier
